# v89 + the two attention KV-loop back-edge targets aligned to 64 bytes (padding sits behind an unconditional branch)
# speedup vs baseline: 1.0005x; 1.0002x over previous
; __device__ __forceinline__ void partialSM(f32x16& p0, f32x16& p1, float& m_reg, float& mn, float& alpha, const float scale) {
;     float pmax = p0[0]; for (int r = 1; r < 16; ++r) pmax = fmaxf(pmax, p0[r]); for (int r = 0; r < 16; ++r) pmax = fmaxf(pmax, p1[r]);
;     { auto rr = __builtin_amdgcn_permlane32_swap(__float_as_uint(pmax), __float_as_uint(pmax), false, false);
;       pmax = fmaxf(__uint_as_float(rr[0]), __uint_as_float(rr[1])); }
;     const float C2 = 1.4426950408889634f * scale;
;     if (__builtin_expect(__all((pmax - m_reg) * scale <= THR), 1)) { mn = m_reg; alpha = 1.f; }
;     else { mn = fmaxf(m_reg, pmax); alpha = __builtin_amdgcn_exp2f((m_reg - mn) * C2); m_reg = mn; }
;     const float mnL = -mn * C2;
;     for (int r = 0; r < 16; ++r) p0[r] = fmaf(p0[r], C2, mnL); for (int r = 0; r < 16; ++r) p1[r] = fmaf(p1[r], C2, mnL);
;     for (int r = 0; r < 16; ++r) p0[r] = __builtin_amdgcn_exp2f(p0[r]);
; }
; template <bool PE, bool SK, bool LSE, bool EARLY>
; __device__ __forceinline__ void swa_block(const BlockRef& cur, const BlockRef& nxt, const Prm& P, char* lds, Seam<PE>& S) {
;     ...
;     const int j_lo = swa_jlo(cur.P0, W);
;     int j_hi = (cur.P0 + QB - 1) / KVBLK + 1; if (j_hi > P.skv / KVBLK) j_hi = P.skv / KVBLK;
;     const int NT = j_hi - j_lo;
;     const int kbn = swa_jlo(nxt.P0, W) * KVBLK;
;     const int qlo = cur.P0 + wid * QBLK, qm = qlo + r32 - 4 * hi;
;     char* V_lds = lds + OFF_V; char* K_lds = lds + OFF_K;
;     float* ws = (float*)(lds + OFF_WS) + wid * 64; float* li_l = ws, * al_l = ws + 32;
;     float m_reg = -1e30f, l_reg = 0; f32x16 o[4] = {};
;     const int sr = tid >> 4, sc = (tid & 15) * 8, vst0 = v_st(sr, sc), vst1 = v_st(32 + sr, sc), kws = KSWZ(sr, sc * 2);
;     const int pr = tid >> 3, pc = (tid & 7) * 8, pws = pr * KPE_ROW + (tid & 7) * 16;
;     const unsigned kvoff = (unsigned)(sr * P.kvs + sc) * 2u, kpoff = (unsigned)(pr * P.kpes + pc) * 2u;
;     const int vb0 = (int)(uintptr_t)lds + v_rd_base(lane);
;     ...
;     f32x16 pA0, pA1, pB0, pB1; float mnA, mnB, alA, alB; bf16x8 pa0, pa1, pa2, pa3;
;     SWRITE_HV(0); SBAR();
;     if (NT > 1) { SLOAD_H(cur, KBASE(1)); }
;     SBAR(); qkt<0, SK, PE>(pA0, pA1, lds, r32, hi, wid, lane, S.qr, ACT(0));
;     MASKT(pA0, pA1, 0); partialSM(pA0, pA1, m_reg, mnA, alA, P.scale);
;     if (NT > 1) { VMW(); SWRITE_H(1); }
;     __syncthreads();
.LBB0_368:
	s_add_i32 s5, s4, 0xff
	s_lshr_b32 s5, s5, 6
	s_add_i32 s5, s5, 1
	s_cmpk_lt_u32 s4, 0xf01
	v_and_b32_e32 v59, 0xf0, v59
	s_movk_i32 s4, 0x90
	s_cselect_b32 s21, s5, 64
	v_bitop3_b32 v59, v60, v62, v59 bitop3:0xde
	v_mad_u64_u32 v[212:213], s[4:5], v61, s4, v[56:57]
	v_lshlrev_b32_e32 v56, 3, v58
	v_and_b32_e32 v60, 0xc0, v63
	v_and_or_b32 v56, v56, 24, v60
	v_lshlrev_b32_e32 v60, 1, v58
	v_lshlrev_b32_e32 v58, 6, v58
	v_and_b32_e32 v60, 32, v60
	v_and_b32_e32 v58, 0x800, v58
	s_cmp_lg_u32 0, -1
	v_or3_b32 v56, v56, v60, v58
	s_cselect_b32 s4, 0, 0
	v_add_u32_e32 v213, s4, v56
	v_max_f32_e32 v56, v21, v21
	v_max_f32_e32 v58, v20, v20
	v_max_f32_e32 v56, v58, v56
	v_max3_f32 v56, v56, v22, v23
	v_max3_f32 v56, v56, v24, v25
	v_max3_f32 v56, v56, v26, v27
	v_max3_f32 v56, v56, v28, v29
	v_max3_f32 v56, v56, v30, v31
	v_max3_f32 v56, v56, v32, v33
	v_max3_f32 v56, v56, v34, v35
	v_max3_f32 v56, v56, v4, v5
	v_max3_f32 v56, v56, v6, v7
	v_max3_f32 v56, v56, v8, v9
	v_max3_f32 v56, v56, v10, v11
	v_max3_f32 v56, v56, v12, v13
	v_max3_f32 v56, v56, v14, v15
	v_max3_f32 v56, v56, v16, v17
	v_max3_f32 v56, v56, v18, v19
	v_mov_b32_e32 v58, v56
	s_nop 1
	v_permlane32_swap_b32_e32 v56, v58
	v_max_f32_e32 v58, v58, v58
	v_max_f32_e32 v56, v56, v56
	v_max_f32_e32 v56, v56, v58
	v_add_f32_e32 v58, 0x7149f2ca, v56
	v_mul_f32_e32 v58, 0x3d93cd3a, v58
	v_max_f32_e32 v56, 0xf149f2ca, v56
	v_cmp_ge_f32_e32 vcc, s35, v58
	v_sub_f32_e32 v58, 0xf149f2ca, v56
	s_add_i32 s23, s1, 0xfffff01f
	v_mul_f32_e32 v58, 0x3dd53b94, v58
	v_exp_f32_e32 v58, v58
	s_cmp_eq_u64 vcc, exec
	s_cselect_b64 vcc, -1, 0
	v_cndmask_b32_e32 v185, v56, v229, vcc
	v_mul_f32_e32 v56, 0xbdd53b94, v185
	v_cndmask_b32_e64 v184, v58, 1.0, vcc
	v_mov_b32_e32 v58, v56
	s_add_i32 s4, 0, 0x12c00
	v_mul_u32_u24_e32 v64, 0x90, v218
	v_fmamk_f32 v20, v20, 0x3dd53b94, v56
	v_fmamk_f32 v21, v21, 0x3dd53b94, v56
	v_fmamk_f32 v22, v22, 0x3dd53b94, v56
	v_fmamk_f32 v23, v23, 0x3dd53b94, v56
	v_fmamk_f32 v24, v24, 0x3dd53b94, v56
	v_fmamk_f32 v25, v25, 0x3dd53b94, v56
	v_fmamk_f32 v26, v26, 0x3dd53b94, v56
	v_fmamk_f32 v27, v27, 0x3dd53b94, v56
	v_fmamk_f32 v28, v28, 0x3dd53b94, v56
	v_fmamk_f32 v29, v29, 0x3dd53b94, v56
	v_fmamk_f32 v30, v30, 0x3dd53b94, v56
	v_fmamk_f32 v31, v31, 0x3dd53b94, v56
	v_fmamk_f32 v32, v32, 0x3dd53b94, v56
	v_fmamk_f32 v33, v33, 0x3dd53b94, v56
	v_fmamk_f32 v34, v34, 0x3dd53b94, v56
	v_fmac_f32_e32 v58, 0x3dd53b94, v35
	v_pk_fma_f32 v[182:183], v[4:5], s[46:47], v[56:57] op_sel_hi:[1,0,0]
	v_add_u32_e32 v216, 0, v59
	v_add_u32_e32 v4, s4, v212
	v_exp_f32_e32 v236, v20
	v_exp_f32_e32 v237, v21
	v_exp_f32_e32 v199, v22
	v_exp_f32_e32 v235, v23
	v_exp_f32_e32 v197, v24
	v_exp_f32_e32 v214, v25
	v_exp_f32_e32 v196, v26
	v_exp_f32_e32 v198, v27
	v_exp_f32_e32 v193, v28
	v_exp_f32_e32 v195, v29
	v_exp_f32_e32 v191, v30
	v_exp_f32_e32 v194, v31
	v_exp_f32_e32 v188, v32
	v_exp_f32_e32 v192, v33
	v_exp_f32_e32 v187, v34
	v_exp_f32_e32 v189, v58
	s_waitcnt vmcnt(0)
	ds_write_b128 v223, v[36:39] offset:16384
	ds_write_b128 v224, v[40:43] offset:16384
	ds_write_b128 v216, v[44:47] offset:49152
	ds_write_b128 v216, v[48:51] offset:57344
	ds_write_b128 v4, v[52:55]
	v_add_u32_e32 v4, s4, v64
	s_add_i32 s4, s1, 0xffffff45
	v_add_u32_e32 v5, s4, v218
	v_mov_b32_e32 v52, v201
	v_mov_b32_e32 v53, v201
	v_pk_fma_f32 v[168:169], v[18:19], s[46:47], v[56:57] op_sel_hi:[1,0,0]
	v_pk_fma_f32 v[170:171], v[16:17], s[46:47], v[56:57] op_sel_hi:[1,0,0]
	v_pk_fma_f32 v[172:173], v[14:15], s[46:47], v[56:57] op_sel_hi:[1,0,0]
	v_pk_fma_f32 v[174:175], v[12:13], s[46:47], v[56:57] op_sel_hi:[1,0,0]
	v_pk_fma_f32 v[176:177], v[10:11], s[46:47], v[56:57] op_sel_hi:[1,0,0]
	v_pk_fma_f32 v[178:179], v[8:9], s[46:47], v[56:57] op_sel_hi:[1,0,0]
	v_pk_fma_f32 v[180:181], v[6:7], s[46:47], v[56:57] op_sel_hi:[1,0,0]
	v_sub_u32_e32 v234, v5, v57
	v_mov_b32_e32 v54, v201
	v_mov_b32_e32 v55, v201
	v_mov_b32_e32 v56, v201
	v_mov_b32_e32 v57, v201
	v_mov_b32_e32 v58, v201
	v_mov_b32_e32 v59, v201
	v_mov_b32_e32 v60, v201
	v_mov_b32_e32 v61, v201
	v_mov_b32_e32 v62, v201
	v_mov_b32_e32 v63, v201
	v_mov_b32_e32 v64, v201
	v_mov_b32_e32 v65, v201
	v_mov_b32_e32 v66, v201
	v_mov_b32_e32 v67, v201
	v_add_u32_e32 v233, v4, v3
	v_mov_b64_e32 v[36:37], v[52:53]
	v_mov_b64_e32 v[20:21], v[52:53]
	v_mov_b64_e32 v[4:5], v[52:53]
	v_mov_b32_e32 v186, 0
	s_movk_i32 s42, 0xbf
	s_mov_b32 s52, 2
	s_movk_i32 s24, 0x180
	v_mov_b64_e32 v[38:39], v[54:55]
	v_mov_b64_e32 v[40:41], v[56:57]
	v_mov_b64_e32 v[42:43], v[58:59]
	v_mov_b64_e32 v[44:45], v[60:61]
	v_mov_b64_e32 v[46:47], v[62:63]
	v_mov_b64_e32 v[48:49], v[64:65]
	v_mov_b64_e32 v[50:51], v[66:67]
	v_mov_b64_e32 v[22:23], v[54:55]
	v_mov_b64_e32 v[24:25], v[56:57]
	v_mov_b64_e32 v[26:27], v[58:59]
	v_mov_b64_e32 v[28:29], v[60:61]
	v_mov_b64_e32 v[30:31], v[62:63]
	v_mov_b64_e32 v[32:33], v[64:65]
	v_mov_b64_e32 v[34:35], v[66:67]
	v_mov_b64_e32 v[6:7], v[54:55]
	v_mov_b64_e32 v[8:9], v[56:57]
	v_mov_b64_e32 v[10:11], v[58:59]
	v_mov_b64_e32 v[12:13], v[60:61]
	v_mov_b64_e32 v[14:15], v[62:63]
	v_mov_b64_e32 v[16:17], v[64:65]
	v_mov_b64_e32 v[18:19], v[66:67]
	s_waitcnt lgkmcnt(0)
	s_barrier
	s_branch .LBB0_370
	.p2align	6

; #define SBAR() __builtin_amdgcn_sched_barrier(0)
; __device__ __forceinline__ void partialSM(f32x16& p0, f32x16& p1, float& m_reg, float& mn, float& alpha, const float scale) {
;     float pmax = p0[0]; for (int r = 1; r < 16; ++r) pmax = fmaxf(pmax, p0[r]); for (int r = 0; r < 16; ++r) pmax = fmaxf(pmax, p1[r]);
;     { auto rr = __builtin_amdgcn_permlane32_swap(__float_as_uint(pmax), __float_as_uint(pmax), false, false);
;       pmax = fmaxf(__uint_as_float(rr[0]), __uint_as_float(rr[1])); }
;     const float C2 = 1.4426950408889634f * scale;
;     if (__builtin_expect(__all((pmax - m_reg) * scale <= THR), 1)) { mn = m_reg; alpha = 1.f; }
;     else { mn = fmaxf(m_reg, pmax); alpha = __builtin_amdgcn_exp2f((m_reg - mn) * C2); m_reg = mn; }
;     const float mnL = -mn * C2;
;     for (int r = 0; r < 16; ++r) p0[r] = fmaf(p0[r], C2, mnL); for (int r = 0; r < 16; ++r) p1[r] = fmaf(p1[r], C2, mnL);
; template <bool PE, bool SK, bool LSE, bool EARLY>
; __device__ __forceinline__ void swa_block(const BlockRef& cur, const BlockRef& nxt, const Prm& P, char* lds, Seam<PE>& S) {
;     ...
;     const int j_lo = swa_jlo(cur.P0, W);
;     int j_hi = (cur.P0 + QB - 1) / KVBLK + 1; if (j_hi > P.skv / KVBLK) j_hi = P.skv / KVBLK;
;     const int NT = j_hi - j_lo;
;     const int kbn = swa_jlo(nxt.P0, W) * KVBLK;
;     const int qlo = cur.P0 + wid * QBLK, qm = qlo + r32 - 4 * hi;
;     char* V_lds = lds + OFF_V; char* K_lds = lds + OFF_K;
;     float* ws = (float*)(lds + OFF_WS) + wid * 64; float* li_l = ws, * al_l = ws + 32;
;     float m_reg = -1e30f, l_reg = 0; f32x16 o[4] = {};
;     const int sr = tid >> 4, sc = (tid & 15) * 8, vst0 = v_st(sr, sc), vst1 = v_st(32 + sr, sc), kws = KSWZ(sr, sc * 2);
;     const int pr = tid >> 3, pc = (tid & 7) * 8, pws = pr * KPE_ROW + (tid & 7) * 16;
;     const unsigned kvoff = (unsigned)(sr * P.kvs + sc) * 2u, kpoff = (unsigned)(pr * P.kpes + pc) * 2u;
;     const int vb0 = (int)(uintptr_t)lds + v_rd_base(lane);
;     ...
;     f32x16 pA0, pA1, pB0, pB1; float mnA, mnB, alA, alB; bf16x8 pa0, pa1, pa2, pa3;
;     SWRITE_HV(0); SBAR();
;     if (NT > 1) { SLOAD_H(cur, KBASE(1)); }
;     SBAR(); qkt<0, SK, PE>(pA0, pA1, lds, r32, hi, wid, lane, S.qr, ACT(0));
;     MASKT(pA0, pA1, 0); partialSM(pA0, pA1, m_reg, mnA, alA, P.scale);
;     if (NT > 1) { VMW(); SWRITE_H(1); }
;     __syncthreads();
;     ...
;     for (int t = 1; t + 1 < NT; t += 2) {
.LBB0_832:
	v_max_f32_e32 v5, 0xf149f2ca, v4
	v_cndmask_b32_e64 v195, v5, v229, s[8:9]
	v_sub_f32_e32 v5, 0xf149f2ca, v5
	v_mul_f32_e32 v5, 0x3e0293ee, v5
	v_exp_f32_e32 v5, v5
	v_and_b32_e32 v199, 63, v50
	v_mul_f32_e32 v4, 0xbe0293ee, v195
	v_fmamk_f32 v6, v34, 0x3e0293ee, v4
	v_cndmask_b32_e64 v194, v5, 1.0, s[8:9]
	v_pk_fma_f32 v[130:131], v[32:33], s[64:65], v[4:5] op_sel_hi:[1,0,0]
	v_pk_fma_f32 v[132:133], v[30:31], s[64:65], v[4:5] op_sel_hi:[1,0,0]
	v_pk_fma_f32 v[134:135], v[28:29], s[64:65], v[4:5] op_sel_hi:[1,0,0]
	v_pk_fma_f32 v[136:137], v[26:27], s[64:65], v[4:5] op_sel_hi:[1,0,0]
	v_pk_fma_f32 v[138:139], v[24:25], s[64:65], v[4:5] op_sel_hi:[1,0,0]
	v_pk_fma_f32 v[140:141], v[22:23], s[64:65], v[4:5] op_sel_hi:[1,0,0]
	v_pk_fma_f32 v[142:143], v[20:21], s[64:65], v[4:5] op_sel_hi:[1,0,0]
	v_pk_fma_f32 v[144:145], v[18:19], s[64:65], v[4:5] op_sel_hi:[1,0,0]
	v_lshlrev_b32_e32 v5, 4, v199
	v_fmamk_f32 v7, v35, 0x3e0293ee, v4
	v_fmamk_f32 v8, v36, 0x3e0293ee, v4
	v_fmamk_f32 v9, v37, 0x3e0293ee, v4
	v_fmamk_f32 v10, v38, 0x3e0293ee, v4
	v_fmamk_f32 v11, v39, 0x3e0293ee, v4
	v_fmamk_f32 v12, v40, 0x3e0293ee, v4
	v_fmamk_f32 v13, v41, 0x3e0293ee, v4
	v_fmamk_f32 v14, v42, 0x3e0293ee, v4
	v_fmamk_f32 v15, v43, 0x3e0293ee, v4
	v_fmamk_f32 v16, v44, 0x3e0293ee, v4
	v_fmamk_f32 v17, v45, 0x3e0293ee, v4
	v_fmamk_f32 v34, v46, 0x3e0293ee, v4
	v_fmamk_f32 v35, v47, 0x3e0293ee, v4
	v_fmamk_f32 v36, v48, 0x3e0293ee, v4
	v_fmamk_f32 v37, v49, 0x3e0293ee, v4
	v_lshlrev_b32_e32 v4, 3, v199
	v_and_b32_e32 v5, 0xc0, v5
	v_exp_f32_e32 v239, v6
	v_exp_f32_e32 v241, v7
	v_exp_f32_e32 v237, v8
	v_exp_f32_e32 v240, v9
	v_exp_f32_e32 v234, v10
	v_exp_f32_e32 v238, v11
	v_exp_f32_e32 v225, v12
	v_exp_f32_e32 v235, v13
	v_exp_f32_e32 v222, v14
	v_exp_f32_e32 v232, v15
	v_exp_f32_e32 v198, v16
	v_exp_f32_e32 v223, v17
	v_exp_f32_e32 v197, v34
	v_exp_f32_e32 v236, v35
	v_exp_f32_e32 v224, v36
	v_exp_f32_e32 v233, v37
	v_and_or_b32 v4, v4, 24, v5
	v_lshlrev_b32_e32 v5, 1, v199
	v_lshlrev_b32_e32 v6, 6, v199
	v_and_b32_e32 v5, 32, v5
	v_and_b32_e32 v6, 0x800, v6
	s_cmp_lg_u32 0, -1
	v_or3_b32 v4, v4, v5, v6
	s_cselect_b32 s8, 0, 0
	v_add_u32_e32 v211, s8, v4
	s_cmp_lt_i32 s23, 3
	s_waitcnt lgkmcnt(0)
	s_barrier
	s_cbranch_scc1 .LBB0_859
	v_lshlrev_b32_e32 v5, 4, v213
	v_and_b32_e32 v5, 0x70, v5
	v_or_b32_e32 v7, 32, v214
	v_or_b32_e32 v8, 64, v214
	v_or_b32_e32 v9, 0x60, v214
	s_add_i32 s8, s20, 0xffffff45
	v_xad_u32 v6, v214, v5, 0
	v_xad_u32 v7, v7, v5, 0
	v_xad_u32 v8, v8, v5, 0
	v_xad_u32 v5, v9, v5, 0
	v_add_u32_e32 v9, s8, v213
	v_mov_b32_e32 v32, v201
	v_mov_b32_e32 v33, v201
	v_and_b32_e32 v4, 8, v213
	v_lshlrev_b32_e32 v4, 4, v4
	v_lshl_or_b32 v4, v213, 8, v4
	v_sub_u32_e32 v3, v9, v3
	s_lshl_b32 s8, s12, 7
	v_mov_b32_e32 v18, v201
	v_mov_b32_e32 v19, v201
	v_mov_b32_e32 v20, v201
	v_mov_b32_e32 v21, v201
	v_mov_b32_e32 v22, v201
	v_mov_b32_e32 v23, v201
	v_mov_b32_e32 v24, v201
	v_mov_b32_e32 v25, v201
	v_mov_b32_e32 v26, v201
	v_mov_b32_e32 v27, v201
	v_mov_b32_e32 v28, v201
	v_mov_b32_e32 v29, v201
	v_mov_b32_e32 v30, v201
	v_mov_b32_e32 v31, v201
	v_mov_b64_e32 v[48:49], v[32:33]
	v_mov_b64_e32 v[64:65], v[32:33]
	v_mov_b64_e32 v[80:81], v[32:33]
	s_add_i32 s53, s20, 0xffffff9e
	s_add_i32 s54, s13, 0xbf
	v_subrev_u32_e32 v217, s13, v3
	s_add_i32 s24, s8, 0x180
	v_mov_b32_e32 v196, 0
	s_mov_b32 s55, 2
	v_add_u32_e32 v218, v6, v4
	v_add_u32_e32 v219, v7, v4
	v_add_u32_e32 v220, v8, v4
	v_add_u32_e32 v221, v5, v4
	v_mov_b64_e32 v[46:47], v[30:31]
	v_mov_b64_e32 v[44:45], v[28:29]
	v_mov_b64_e32 v[42:43], v[26:27]
	v_mov_b64_e32 v[40:41], v[24:25]
	v_mov_b64_e32 v[38:39], v[22:23]
	v_mov_b64_e32 v[36:37], v[20:21]
	v_mov_b64_e32 v[34:35], v[18:19]
	v_mov_b64_e32 v[62:63], v[30:31]
	v_mov_b64_e32 v[60:61], v[28:29]
	v_mov_b64_e32 v[58:59], v[26:27]
	v_mov_b64_e32 v[56:57], v[24:25]
	v_mov_b64_e32 v[54:55], v[22:23]
	v_mov_b64_e32 v[52:53], v[20:21]
	v_mov_b64_e32 v[50:51], v[18:19]
	v_mov_b64_e32 v[78:79], v[30:31]
	v_mov_b64_e32 v[76:77], v[28:29]
	v_mov_b64_e32 v[74:75], v[26:27]
	v_mov_b64_e32 v[72:73], v[24:25]
	v_mov_b64_e32 v[70:71], v[22:23]
	v_mov_b64_e32 v[68:69], v[20:21]
	v_mov_b64_e32 v[66:67], v[18:19]
	s_branch .LBB0_835
	.p2align	6
